# v034 + hand-written grid barrier at seams 1-4 (leader posts non-returning add, everyone polls the cross-XCD arrival counter; no TOPGEN/XGEN hops, no division emulation)
# speedup vs baseline: 1.0034x; 1.0034x over previous
; __device__ __forceinline__ unsigned xb_ld(unsigned* p)              { return __hip_atomic_load(p, __ATOMIC_RELAXED, __HIP_MEMORY_SCOPE_AGENT); }
; __device__ __forceinline__ unsigned xb_add(unsigned* p, unsigned v) { return __hip_atomic_fetch_add(p, v, __ATOMIC_RELAXED, __HIP_MEMORY_SCOPE_AGENT); }
; #define XB_SPIN(cond, bar) do { unsigned _sp = 0; while (cond) { __builtin_amdgcn_s_sleep(1); \
;     if ((++_sp & 255u) == 0u) { if (xb_ld(&(bar)[XB_TMO])) break; if (_sp > XB_SPIN_CAP) { atomicAdd(&(bar)[XB_TMO], 1u); break; } } } } while (0)
; __device__ __forceinline__ void xcd_barrier(const XcdBarrier& b) {
;     asm volatile("s_waitcnt vmcnt(0)" ::: "memory");
;     __syncthreads();
;     if (threadIdx.x == 0) {
;         unsigned* bar = b.bar;
;         __builtin_amdgcn_s_waitcnt(0);
;         unsigned nloc = b.st[0], nx = b.st[1];
;         if (nloc == 0u) { xcd_barrier_complete(bar, b.x, nloc, nx); b.st[0] = nloc; b.st[1] = nx; }
;         const unsigned old = xb_add(&bar[XB_XSUB(b.x)], 1u);
;         const unsigned gen = old / nloc;
;         if (old + 1u == (gen + 1u) * nloc) {
;             __builtin_amdgcn_fence(__ATOMIC_RELEASE, "agent");
;             asm volatile("s_waitcnt vmcnt(0)" ::: "memory");
;             const unsigned og = xb_add(&bar[XB_TOP], 1u);
;             const unsigned tg = og / nx;
;             if (og + 1u == (tg + 1u) * nx) xb_add(&bar[XB_TOPGEN], 1u);
;             else XB_SPIN(xb_ld(&bar[XB_TOPGEN]) == tg, bar);
;             __builtin_amdgcn_fence(__ATOMIC_ACQUIRE, "agent");
;             xb_add(&bar[XB_XGEN(b.x)], 1u);
;             asm volatile("s_waitcnt vmcnt(0)" ::: "memory");
;         } else {
;             XB_SPIN(xb_ld(&bar[XB_XGEN(b.x)]) == gen, bar);
;             __builtin_amdgcn_fence(__ATOMIC_ACQUIRE, "agent");
;             asm volatile("s_waitcnt vmcnt(0)" ::: "memory");
;         }
;     }
;     __syncthreads();
; }
.LBB0_133:
	s_cmp_lt_i32 s27, 3
	s_cbranch_scc1 .LBB0_183
	s_waitcnt vmcnt(0) lgkmcnt(0)
	s_barrier
	v_cmp_eq_u32_e32 vcc, 0, v0
	s_and_saveexec_b64 s[0:1], vcc
	s_cbranch_execz .Lgb1_join
	v_mov_b32_e32 v1, s85
	ds_read_b32 v2, v1
	ds_read_b32 v3, v1 offset:4
	s_lshl_b32 s4, s84, 8
	s_add_u32 s4, s22, s4
	s_addc_u32 s5, s23, 0
	v_mov_b32_e32 v4, 0x1000
	v_mov_b32_e32 v5, 1
	global_atomic_add v5, v4, v5, s[4:5] offset:1024 sc0
	s_waitcnt lgkmcnt(0)
	v_readfirstlane_b32 s6, v2
	v_readfirstlane_b32 s7, v3
	s_nop 3
	s_mul_i32 s14, s6, 2
	s_add_i32 s14, s14, -1
	s_mul_i32 s7, s7, 2
	s_waitcnt vmcnt(0)
	v_readfirstlane_b32 s15, v5
	v_mov_b32_e32 v4, 0x3400
	s_nop 3
	s_cmp_lg_u32 s15, s14
	s_cbranch_scc1 .Lgb1_poll
	buffer_wbl2 sc1
	s_waitcnt vmcnt(0)
	v_mov_b32_e32 v5, 1
	global_atomic_add v4, v5, s[22:23]
.Lgb1_poll:
	s_mov_b32 s11, 0
.Lgb1_spin:
	global_load_dword v5, v4, s[22:23] sc1
	s_waitcnt vmcnt(0)
	v_readfirstlane_b32 s15, v5
	s_nop 3
	s_cmp_ge_u32 s15, s7
	s_cbranch_scc1 .Lgb1_acq
	s_sleep 1
	s_add_i32 s11, s11, 1
	s_cmp_lt_u32 s11, 0x8000
	s_cbranch_scc1 .Lgb1_spin
.Lgb1_acq:
	buffer_inv sc1
	s_waitcnt vmcnt(0)
.Lgb1_join:
	s_or_b64 exec, exec, s[0:1]
	s_barrier

; __device__ __forceinline__ unsigned xb_ld(unsigned* p)              { return __hip_atomic_load(p, __ATOMIC_RELAXED, __HIP_MEMORY_SCOPE_AGENT); }
; __device__ __forceinline__ unsigned xb_add(unsigned* p, unsigned v) { return __hip_atomic_fetch_add(p, v, __ATOMIC_RELAXED, __HIP_MEMORY_SCOPE_AGENT); }
; #define XB_SPIN(cond, bar) do { unsigned _sp = 0; while (cond) { __builtin_amdgcn_s_sleep(1); \
;     if ((++_sp & 255u) == 0u) { if (xb_ld(&(bar)[XB_TMO])) break; if (_sp > XB_SPIN_CAP) { atomicAdd(&(bar)[XB_TMO], 1u); break; } } } } while (0)
; __device__ __forceinline__ void xcd_barrier(const XcdBarrier& b) {
;     asm volatile("s_waitcnt vmcnt(0)" ::: "memory");
;     __syncthreads();
;     if (threadIdx.x == 0) {
;         unsigned* bar = b.bar;
;         __builtin_amdgcn_s_waitcnt(0);
;         unsigned nloc = b.st[0], nx = b.st[1];
;         if (nloc == 0u) { xcd_barrier_complete(bar, b.x, nloc, nx); b.st[0] = nloc; b.st[1] = nx; }
;         const unsigned old = xb_add(&bar[XB_XSUB(b.x)], 1u);
;         const unsigned gen = old / nloc;
;         if (old + 1u == (gen + 1u) * nloc) {
;             __builtin_amdgcn_fence(__ATOMIC_RELEASE, "agent");
;             asm volatile("s_waitcnt vmcnt(0)" ::: "memory");
;             const unsigned og = xb_add(&bar[XB_TOP], 1u);
;             const unsigned tg = og / nx;
;             if (og + 1u == (tg + 1u) * nx) xb_add(&bar[XB_TOPGEN], 1u);
;             else XB_SPIN(xb_ld(&bar[XB_TOPGEN]) == tg, bar);
;             __builtin_amdgcn_fence(__ATOMIC_ACQUIRE, "agent");
;             xb_add(&bar[XB_XGEN(b.x)], 1u);
;             asm volatile("s_waitcnt vmcnt(0)" ::: "memory");
;         } else {
;             XB_SPIN(xb_ld(&bar[XB_XGEN(b.x)]) == gen, bar);
;             __builtin_amdgcn_fence(__ATOMIC_ACQUIRE, "agent");
;             asm volatile("s_waitcnt vmcnt(0)" ::: "memory");
;         }
;     }
;     __syncthreads();
; }
.LBB0_395:
	s_waitcnt vmcnt(0) lgkmcnt(0)
	s_barrier
	v_cmp_eq_u32_e32 vcc, 0, v0
	s_and_saveexec_b64 s[0:1], vcc
	s_cbranch_execz .Lgb2_join
	v_mov_b32_e32 v1, s85
	ds_read_b32 v2, v1
	ds_read_b32 v3, v1 offset:4
	s_lshl_b32 s4, s84, 8
	s_add_u32 s4, s22, s4
	s_addc_u32 s5, s23, 0
	v_mov_b32_e32 v4, 0x1000
	v_mov_b32_e32 v5, 1
	global_atomic_add v5, v4, v5, s[4:5] offset:1024 sc0
	s_waitcnt lgkmcnt(0)
	v_readfirstlane_b32 s6, v2
	v_readfirstlane_b32 s7, v3
	s_nop 3
	s_mul_i32 s14, s6, 3
	s_add_i32 s14, s14, -1
	s_mul_i32 s7, s7, 3
	s_waitcnt vmcnt(0)
	v_readfirstlane_b32 s15, v5
	v_mov_b32_e32 v4, 0x3400
	s_nop 3
	s_cmp_lg_u32 s15, s14
	s_cbranch_scc1 .Lgb2_poll
	buffer_wbl2 sc1
	s_waitcnt vmcnt(0)
	v_mov_b32_e32 v5, 1
	global_atomic_add v4, v5, s[22:23]

; __device__ __forceinline__ unsigned xb_ld(unsigned* p)              { return __hip_atomic_load(p, __ATOMIC_RELAXED, __HIP_MEMORY_SCOPE_AGENT); }
; __device__ __forceinline__ unsigned xb_add(unsigned* p, unsigned v) { return __hip_atomic_fetch_add(p, v, __ATOMIC_RELAXED, __HIP_MEMORY_SCOPE_AGENT); }
; #define XB_SPIN(cond, bar) do { unsigned _sp = 0; while (cond) { __builtin_amdgcn_s_sleep(1); \
;     if ((++_sp & 255u) == 0u) { if (xb_ld(&(bar)[XB_TMO])) break; if (_sp > XB_SPIN_CAP) { atomicAdd(&(bar)[XB_TMO], 1u); break; } } } } while (0)
; __device__ __forceinline__ void xcd_barrier(const XcdBarrier& b) {
;     asm volatile("s_waitcnt vmcnt(0)" ::: "memory");
;     __syncthreads();
;     if (threadIdx.x == 0) {
;         unsigned* bar = b.bar;
;         __builtin_amdgcn_s_waitcnt(0);
;         unsigned nloc = b.st[0], nx = b.st[1];
;         if (nloc == 0u) { xcd_barrier_complete(bar, b.x, nloc, nx); b.st[0] = nloc; b.st[1] = nx; }
;         const unsigned old = xb_add(&bar[XB_XSUB(b.x)], 1u);
;         const unsigned gen = old / nloc;
;         if (old + 1u == (gen + 1u) * nloc) {
;             __builtin_amdgcn_fence(__ATOMIC_RELEASE, "agent");
;             asm volatile("s_waitcnt vmcnt(0)" ::: "memory");
;             const unsigned og = xb_add(&bar[XB_TOP], 1u);
;             const unsigned tg = og / nx;
;             if (og + 1u == (tg + 1u) * nx) xb_add(&bar[XB_TOPGEN], 1u);
;             else XB_SPIN(xb_ld(&bar[XB_TOPGEN]) == tg, bar);
;             __builtin_amdgcn_fence(__ATOMIC_ACQUIRE, "agent");
;             xb_add(&bar[XB_XGEN(b.x)], 1u);
;             asm volatile("s_waitcnt vmcnt(0)" ::: "memory");
;         } else {
;             XB_SPIN(xb_ld(&bar[XB_XGEN(b.x)]) == gen, bar);
;             __builtin_amdgcn_fence(__ATOMIC_ACQUIRE, "agent");
;             asm volatile("s_waitcnt vmcnt(0)" ::: "memory");
;         }
;     }
;     __syncthreads();
; }
.LBB0_679:
	s_cmp_lt_i32 s27, 5
	s_cbranch_scc1 .LBB0_729
	s_waitcnt vmcnt(0) lgkmcnt(0)
	s_barrier
	v_cmp_eq_u32_e32 vcc, 0, v0
	s_and_saveexec_b64 s[0:1], vcc
	s_cbranch_execz .Lgb3_join
	v_mov_b32_e32 v1, s85
	ds_read_b32 v2, v1
	ds_read_b32 v3, v1 offset:4
	s_lshl_b32 s4, s84, 8
	s_add_u32 s4, s22, s4
	s_addc_u32 s5, s23, 0
	v_mov_b32_e32 v4, 0x1000
	v_mov_b32_e32 v5, 1
	global_atomic_add v5, v4, v5, s[4:5] offset:1024 sc0
	s_waitcnt lgkmcnt(0)
	v_readfirstlane_b32 s6, v2
	v_readfirstlane_b32 s7, v3
	s_nop 3
	s_mul_i32 s14, s6, 4
	s_add_i32 s14, s14, -1
	s_mul_i32 s7, s7, 4
	s_waitcnt vmcnt(0)
	v_readfirstlane_b32 s15, v5
	v_mov_b32_e32 v4, 0x3400
	s_nop 3
	s_cmp_lg_u32 s15, s14
	s_cbranch_scc1 .Lgb3_poll
	buffer_wbl2 sc1
	s_waitcnt vmcnt(0)
	v_mov_b32_e32 v5, 1
	global_atomic_add v4, v5, s[22:23]

; __device__ __forceinline__ unsigned xb_ld(unsigned* p)              { return __hip_atomic_load(p, __ATOMIC_RELAXED, __HIP_MEMORY_SCOPE_AGENT); }
; __device__ __forceinline__ unsigned xb_add(unsigned* p, unsigned v) { return __hip_atomic_fetch_add(p, v, __ATOMIC_RELAXED, __HIP_MEMORY_SCOPE_AGENT); }
; #define XB_SPIN(cond, bar) do { unsigned _sp = 0; while (cond) { __builtin_amdgcn_s_sleep(1); \
;     if ((++_sp & 255u) == 0u) { if (xb_ld(&(bar)[XB_TMO])) break; if (_sp > XB_SPIN_CAP) { atomicAdd(&(bar)[XB_TMO], 1u); break; } } } } while (0)
; __device__ __forceinline__ void xcd_barrier(const XcdBarrier& b) {
;     asm volatile("s_waitcnt vmcnt(0)" ::: "memory");
;     __syncthreads();
;     if (threadIdx.x == 0) {
;         unsigned* bar = b.bar;
;         __builtin_amdgcn_s_waitcnt(0);
;         unsigned nloc = b.st[0], nx = b.st[1];
;         if (nloc == 0u) { xcd_barrier_complete(bar, b.x, nloc, nx); b.st[0] = nloc; b.st[1] = nx; }
;         const unsigned old = xb_add(&bar[XB_XSUB(b.x)], 1u);
;         const unsigned gen = old / nloc;
;         if (old + 1u == (gen + 1u) * nloc) {
;             __builtin_amdgcn_fence(__ATOMIC_RELEASE, "agent");
;             asm volatile("s_waitcnt vmcnt(0)" ::: "memory");
;             const unsigned og = xb_add(&bar[XB_TOP], 1u);
;             const unsigned tg = og / nx;
;             if (og + 1u == (tg + 1u) * nx) xb_add(&bar[XB_TOPGEN], 1u);
;             else XB_SPIN(xb_ld(&bar[XB_TOPGEN]) == tg, bar);
;             __builtin_amdgcn_fence(__ATOMIC_ACQUIRE, "agent");
;             xb_add(&bar[XB_XGEN(b.x)], 1u);
;             asm volatile("s_waitcnt vmcnt(0)" ::: "memory");
;         } else {
;             XB_SPIN(xb_ld(&bar[XB_XGEN(b.x)]) == gen, bar);
;             __builtin_amdgcn_fence(__ATOMIC_ACQUIRE, "agent");
;             asm volatile("s_waitcnt vmcnt(0)" ::: "memory");
;         }
;     }
;     __syncthreads();
; }
.LBB0_787:
	s_waitcnt vmcnt(0) lgkmcnt(0)
	s_barrier
	v_cmp_eq_u32_e32 vcc, 0, v0
	s_and_saveexec_b64 s[0:1], vcc
	s_cbranch_execz .Lgb4_join
	v_mov_b32_e32 v1, s85
	ds_read_b32 v2, v1
	ds_read_b32 v3, v1 offset:4
	s_lshl_b32 s4, s84, 8
	s_add_u32 s4, s22, s4
	s_addc_u32 s5, s23, 0
	v_mov_b32_e32 v4, 0x1000
	v_mov_b32_e32 v5, 1
	global_atomic_add v5, v4, v5, s[4:5] offset:1024 sc0
	s_waitcnt lgkmcnt(0)
	v_readfirstlane_b32 s6, v2
	v_readfirstlane_b32 s7, v3
	s_nop 3
	s_mul_i32 s14, s6, 5
	s_add_i32 s14, s14, -1
	s_mul_i32 s7, s7, 5
	s_waitcnt vmcnt(0)
	v_readfirstlane_b32 s15, v5
	v_mov_b32_e32 v4, 0x3400
	s_nop 3
	s_cmp_lg_u32 s15, s14
	s_cbranch_scc1 .Lgb4_poll
	buffer_wbl2 sc1
	s_waitcnt vmcnt(0)
	v_mov_b32_e32 v5, 1
	global_atomic_add v4, v5, s[22:23]
